# A2 stores in out-proj epilogue without nt hint (keep A2 cache-resident for the FFN-in GEMM)
# speedup vs baseline: 1.0069x; 1.0069x over previous
.LBB0_618:
	ds_read_b128 v[48:51], v185
	ds_read_b128 v[52:55], v185 offset:1024
	ds_read_b128 v[56:59], v185 offset:2048
	ds_read_b128 v[60:63], v185 offset:3072
	s_add_u32 s47, s48, 0xfffc0080
	s_addc_u32 s50, s49, -1
	s_cmp_eq_u32 s35, 12
	s_cselect_b32 s55, s3, s50
	s_cselect_b32 s54, s21, s47
	s_cselect_b32 s53, s22, s33
	s_cselect_b32 s52, s23, s31
	v_lshl_add_u64 v[180:181], s[48:49], 0, v[164:165]
	s_add_i32 m0, s11, 0xc000
	ds_read_b128 v[144:147], v186
	ds_read_b128 v[148:151], v186 offset:1024
	ds_read_b128 v[152:155], v186 offset:2048
	ds_read_b128 v[156:159], v186 offset:3072
	ds_read_b128 v[172:175], v186 offset:4096
	ds_read_b128 v[176:179], v186 offset:5120
	ds_read_b128 v[188:191], v186 offset:6144
	ds_read_b128 v[192:195], v186 offset:7168
	global_load_lds_dwordx4 v[180:181], off
	v_lshl_add_u64 v[180:181], s[48:49], 0, v[166:167]
	s_add_i32 m0, s11, 0xe000
	s_nop 0
	global_load_lds_dwordx4 v[180:181], off
	s_waitcnt lgkmcnt(8)
	s_barrier
	s_waitcnt lgkmcnt(0)
	s_setprio 1
	s_waitcnt lgkmcnt(0)
	v_mfma_f32_16x16x32_bf16 v[140:143], v[48:51], v[144:147], v[140:143]
	v_mfma_f32_16x16x32_bf16 v[136:139], v[56:59], v[144:147], v[136:139]
	v_mfma_f32_16x16x32_bf16 v[124:127], v[48:51], v[152:155], v[124:127]
	v_mfma_f32_16x16x32_bf16 v[120:123], v[56:59], v[152:155], v[120:123]
	v_mfma_f32_16x16x32_bf16 v[108:111], v[48:51], v[172:175], v[108:111]
	v_mfma_f32_16x16x32_bf16 v[104:107], v[56:59], v[172:175], v[104:107]
	v_mfma_f32_16x16x32_bf16 v[92:95], v[48:51], v[188:191], v[92:95]
	v_mfma_f32_16x16x32_bf16 v[88:91], v[56:59], v[188:191], v[88:91]
	v_mfma_f32_16x16x32_bf16 v[140:143], v[52:55], v[148:151], v[140:143]
	v_mfma_f32_16x16x32_bf16 v[136:139], v[60:63], v[148:151], v[136:139]
	v_mfma_f32_16x16x32_bf16 v[124:127], v[52:55], v[156:159], v[124:127]
	v_mfma_f32_16x16x32_bf16 v[120:123], v[60:63], v[156:159], v[120:123]
	v_mfma_f32_16x16x32_bf16 v[108:111], v[52:55], v[176:179], v[108:111]
	v_mfma_f32_16x16x32_bf16 v[104:107], v[60:63], v[176:179], v[104:107]
	v_mfma_f32_16x16x32_bf16 v[92:95], v[52:55], v[192:195], v[92:95]
	v_mfma_f32_16x16x32_bf16 v[88:91], v[60:63], v[192:195], v[88:91]
	s_setprio 0
	s_barrier
	s_add_i32 s47, s19, s10
	v_lshl_add_u64 v[180:181], s[52:53], 0, v[160:161]
	s_mov_b32 m0, s47
	ds_read_b128 v[196:199], v187
	ds_read_b128 v[200:203], v187 offset:1024
	ds_read_b128 v[204:207], v187 offset:2048
	ds_read_b128 v[208:211], v187 offset:3072
	global_load_lds_dwordx4 v[180:181], off
	v_lshl_add_u64 v[212:213], s[52:53], 0, v[162:163]
	s_add_i32 m0, s47, 0x2000
	s_nop 0
	global_load_lds_dwordx4 v[212:213], off
	s_barrier
	s_waitcnt lgkmcnt(0)
	s_setprio 1
	s_waitcnt lgkmcnt(0)
	v_mfma_f32_16x16x32_bf16 v[132:135], v[196:199], v[144:147], v[132:135]
	v_mfma_f32_16x16x32_bf16 v[128:131], v[204:207], v[144:147], v[128:131]
	v_mfma_f32_16x16x32_bf16 v[116:119], v[196:199], v[152:155], v[116:119]
	v_mfma_f32_16x16x32_bf16 v[112:115], v[204:207], v[152:155], v[112:115]
	v_mfma_f32_16x16x32_bf16 v[100:103], v[196:199], v[172:175], v[100:103]
	v_mfma_f32_16x16x32_bf16 v[96:99], v[204:207], v[172:175], v[96:99]
	v_mfma_f32_16x16x32_bf16 v[84:87], v[196:199], v[188:191], v[84:87]
	v_mfma_f32_16x16x32_bf16 v[80:83], v[204:207], v[188:191], v[80:83]
	v_mfma_f32_16x16x32_bf16 v[132:135], v[200:203], v[148:151], v[132:135]
	v_mfma_f32_16x16x32_bf16 v[128:131], v[208:211], v[148:151], v[128:131]
	v_mfma_f32_16x16x32_bf16 v[116:119], v[200:203], v[156:159], v[116:119]
	v_mfma_f32_16x16x32_bf16 v[112:115], v[208:211], v[156:159], v[112:115]
	v_mfma_f32_16x16x32_bf16 v[100:103], v[200:203], v[176:179], v[100:103]
	v_mfma_f32_16x16x32_bf16 v[96:99], v[208:211], v[176:179], v[96:99]
	v_mfma_f32_16x16x32_bf16 v[84:87], v[200:203], v[192:195], v[84:87]
	v_mfma_f32_16x16x32_bf16 v[80:83], v[208:211], v[192:195], v[80:83]
	s_setprio 0
	s_mov_b32 m0, s11
	v_lshl_add_u64 v[214:215], s[54:55], 0, v[160:161]
	s_barrier
	ds_read_b128 v[144:147], v186 offset:16384
	ds_read_b128 v[148:151], v186 offset:17408
	ds_read_b128 v[152:155], v186 offset:18432
	ds_read_b128 v[156:159], v186 offset:19456
	ds_read_b128 v[172:175], v186 offset:20480
	ds_read_b128 v[176:179], v186 offset:21504
	ds_read_b128 v[188:191], v186 offset:22528
	ds_read_b128 v[192:195], v186 offset:23552
	global_load_lds_dwordx4 v[214:215], off
	v_lshl_add_u64 v[216:217], s[54:55], 0, v[162:163]
	s_mov_b32 m0, s12
	s_nop 0
	global_load_lds_dwordx4 v[216:217], off
	s_barrier
	s_waitcnt lgkmcnt(0)
	s_setprio 1
	s_waitcnt lgkmcnt(0)
	v_mfma_f32_16x16x32_bf16 v[76:79], v[48:51], v[144:147], v[76:79]
	v_mfma_f32_16x16x32_bf16 v[72:75], v[56:59], v[144:147], v[72:75]
	v_mfma_f32_16x16x32_bf16 v[44:47], v[48:51], v[152:155], v[44:47]
	v_mfma_f32_16x16x32_bf16 v[40:43], v[56:59], v[152:155], v[40:43]
	v_mfma_f32_16x16x32_bf16 v[28:31], v[48:51], v[172:175], v[28:31]
	v_mfma_f32_16x16x32_bf16 v[24:27], v[56:59], v[172:175], v[24:27]
	v_mfma_f32_16x16x32_bf16 v[12:15], v[48:51], v[188:191], v[12:15]
	v_mfma_f32_16x16x32_bf16 v[8:11], v[56:59], v[188:191], v[8:11]
	v_mfma_f32_16x16x32_bf16 v[76:79], v[52:55], v[148:151], v[76:79]
	v_mfma_f32_16x16x32_bf16 v[72:75], v[60:63], v[148:151], v[72:75]
	v_mfma_f32_16x16x32_bf16 v[44:47], v[52:55], v[156:159], v[44:47]
	v_mfma_f32_16x16x32_bf16 v[40:43], v[60:63], v[156:159], v[40:43]
	v_mfma_f32_16x16x32_bf16 v[28:31], v[52:55], v[176:179], v[28:31]
	v_mfma_f32_16x16x32_bf16 v[24:27], v[60:63], v[176:179], v[24:27]
	v_mfma_f32_16x16x32_bf16 v[12:15], v[52:55], v[192:195], v[12:15]
	v_mfma_f32_16x16x32_bf16 v[8:11], v[60:63], v[192:195], v[8:11]
	s_setprio 0
	s_barrier
	s_add_u32 s50, s52, 0x40000
	s_addc_u32 s51, s53, 0
	s_add_i32 s47, s20, s10
	v_lshl_add_u64 v[48:49], s[50:51], 0, v[160:161]
	s_mov_b32 m0, s47
	s_nop 0
	global_load_lds_dwordx4 v[48:49], off
	v_lshl_add_u64 v[48:49], s[50:51], 0, v[162:163]
	s_add_i32 m0, s47, 0x2000
	s_nop 0
	global_load_lds_dwordx4 v[48:49], off
	s_waitcnt vmcnt(6)
	s_barrier
	s_setprio 1
	v_mfma_f32_16x16x32_bf16 v[36:39], v[196:199], v[152:155], v[36:39]
	v_mfma_f32_16x16x32_bf16 v[32:35], v[204:207], v[152:155], v[32:35]
	v_mfma_f32_16x16x32_bf16 v[20:23], v[196:199], v[172:175], v[20:23]
	v_mfma_f32_16x16x32_bf16 v[16:19], v[204:207], v[172:175], v[16:19]
	v_mfma_f32_16x16x32_bf16 v[4:7], v[196:199], v[188:191], v[4:7]
	v_mfma_f32_16x16x32_bf16 v[0:3], v[204:207], v[188:191], v[0:3]
	v_mfma_f32_16x16x32_bf16 v[48:51], v[196:199], v[144:147], v[68:71]
	v_mfma_f32_16x16x32_bf16 v[52:55], v[204:207], v[144:147], v[64:67]
	v_mfma_f32_16x16x32_bf16 v[36:39], v[200:203], v[156:159], v[36:39]
	v_mfma_f32_16x16x32_bf16 v[32:35], v[208:211], v[156:159], v[32:35]
	v_mfma_f32_16x16x32_bf16 v[20:23], v[200:203], v[176:179], v[20:23]
	v_mfma_f32_16x16x32_bf16 v[16:19], v[208:211], v[176:179], v[16:19]
	v_mfma_f32_16x16x32_bf16 v[4:7], v[200:203], v[192:195], v[4:7]
	v_mfma_f32_16x16x32_bf16 v[0:3], v[208:211], v[192:195], v[0:3]
	v_mfma_f32_16x16x32_bf16 v[48:51], v[200:203], v[148:151], v[48:51]
	v_mfma_f32_16x16x32_bf16 v[52:55], v[208:211], v[148:151], v[52:55]
	s_setprio 0
	s_add_i32 s47, 0, 0x18000
	v_add_u32_e32 v68, s47, v183
	s_barrier
	ds_read_b128 v[56:59], v68
	ds_read_b128 v[60:63], v68 offset:1024
	ds_read_b128 v[64:67], v68 offset:2048
	ds_read_b128 v[68:71], v68 offset:3072
	s_add_u32 s50, s54, 0x40000
	s_addc_u32 s51, s55, 0
	s_mov_b32 m0, s13
	v_lshl_add_u64 v[196:197], s[50:51], 0, v[160:161]
	ds_read_b128 v[144:147], v186 offset:32768
	ds_read_b128 v[148:151], v186 offset:33792
	ds_read_b128 v[152:155], v186 offset:34816
	ds_read_b128 v[156:159], v186 offset:35840
	ds_read_b128 v[172:175], v186 offset:36864
	ds_read_b128 v[176:179], v186 offset:37888
	ds_read_b128 v[188:191], v186 offset:38912
	ds_read_b128 v[192:195], v186 offset:39936
	global_load_lds_dwordx4 v[196:197], off
	v_lshl_add_u64 v[196:197], s[50:51], 0, v[162:163]
	s_mov_b32 m0, s14
	s_nop 0
	global_load_lds_dwordx4 v[196:197], off
	s_waitcnt lgkmcnt(8)
	s_barrier
	s_waitcnt lgkmcnt(0)
	s_setprio 1
	s_waitcnt lgkmcnt(0)
	v_mfma_f32_16x16x32_bf16 v[140:143], v[56:59], v[144:147], v[140:143]
	v_mfma_f32_16x16x32_bf16 v[136:139], v[64:67], v[144:147], v[136:139]
	v_mfma_f32_16x16x32_bf16 v[124:127], v[56:59], v[152:155], v[124:127]
	v_mfma_f32_16x16x32_bf16 v[120:123], v[64:67], v[152:155], v[120:123]
	v_mfma_f32_16x16x32_bf16 v[108:111], v[56:59], v[172:175], v[108:111]
	v_mfma_f32_16x16x32_bf16 v[104:107], v[64:67], v[172:175], v[104:107]
	v_mfma_f32_16x16x32_bf16 v[92:95], v[56:59], v[188:191], v[92:95]
	v_mfma_f32_16x16x32_bf16 v[88:91], v[64:67], v[188:191], v[88:91]
	v_mfma_f32_16x16x32_bf16 v[140:143], v[60:63], v[148:151], v[140:143]
	v_mfma_f32_16x16x32_bf16 v[136:139], v[68:71], v[148:151], v[136:139]
	v_mfma_f32_16x16x32_bf16 v[124:127], v[60:63], v[156:159], v[124:127]
	v_mfma_f32_16x16x32_bf16 v[120:123], v[68:71], v[156:159], v[120:123]
	v_mfma_f32_16x16x32_bf16 v[108:111], v[60:63], v[176:179], v[108:111]
	v_mfma_f32_16x16x32_bf16 v[104:107], v[68:71], v[176:179], v[104:107]
	v_mfma_f32_16x16x32_bf16 v[92:95], v[60:63], v[192:195], v[92:95]
	v_mfma_f32_16x16x32_bf16 v[88:91], v[68:71], v[192:195], v[88:91]
	s_setprio 0
	s_barrier
	s_add_i32 s54, 0, 0x1c000
	s_add_i32 s47, s47, s10
	v_add_u32_e32 v208, s54, v183
	v_lshl_add_u64 v[180:181], v[180:181], 0, s[28:29]
	s_mov_b32 m0, s47
	ds_read_b128 v[196:199], v208
	ds_read_b128 v[200:203], v208 offset:1024
	ds_read_b128 v[204:207], v208 offset:2048
	ds_read_b128 v[208:211], v208 offset:3072
	global_load_lds_dwordx4 v[180:181], off
	v_lshl_add_u64 v[180:181], v[212:213], 0, s[28:29]
	s_add_i32 m0, s47, 0x2000
	s_nop 0
	global_load_lds_dwordx4 v[180:181], off
	s_barrier
	s_waitcnt lgkmcnt(0)
	s_setprio 1
	s_waitcnt lgkmcnt(0)
	v_mfma_f32_16x16x32_bf16 v[132:135], v[196:199], v[144:147], v[132:135]
	v_mfma_f32_16x16x32_bf16 v[128:131], v[204:207], v[144:147], v[128:131]
	v_mfma_f32_16x16x32_bf16 v[116:119], v[196:199], v[152:155], v[116:119]
	v_mfma_f32_16x16x32_bf16 v[112:115], v[204:207], v[152:155], v[112:115]
	v_mfma_f32_16x16x32_bf16 v[100:103], v[196:199], v[172:175], v[100:103]
	v_mfma_f32_16x16x32_bf16 v[96:99], v[204:207], v[172:175], v[96:99]
	v_mfma_f32_16x16x32_bf16 v[84:87], v[196:199], v[188:191], v[84:87]
	v_mfma_f32_16x16x32_bf16 v[80:83], v[204:207], v[188:191], v[80:83]
	v_mfma_f32_16x16x32_bf16 v[132:135], v[200:203], v[148:151], v[132:135]
	v_mfma_f32_16x16x32_bf16 v[128:131], v[208:211], v[148:151], v[128:131]
	v_mfma_f32_16x16x32_bf16 v[116:119], v[200:203], v[156:159], v[116:119]
	v_mfma_f32_16x16x32_bf16 v[112:115], v[208:211], v[156:159], v[112:115]
	v_mfma_f32_16x16x32_bf16 v[100:103], v[200:203], v[176:179], v[100:103]
	v_mfma_f32_16x16x32_bf16 v[96:99], v[208:211], v[176:179], v[96:99]
	v_mfma_f32_16x16x32_bf16 v[84:87], v[200:203], v[192:195], v[84:87]
	v_mfma_f32_16x16x32_bf16 v[80:83], v[208:211], v[192:195], v[80:83]
	s_setprio 0
	s_mov_b32 m0, s16
	v_lshl_add_u64 v[180:181], v[214:215], 0, s[28:29]
	s_barrier
	ds_read_b128 v[144:147], v186 offset:49152
	ds_read_b128 v[148:151], v186 offset:50176
	ds_read_b128 v[152:155], v186 offset:51200
	ds_read_b128 v[156:159], v186 offset:52224
	ds_read_b128 v[172:175], v186 offset:53248
	ds_read_b128 v[176:179], v186 offset:54272
	ds_read_b128 v[188:191], v186 offset:55296
	ds_read_b128 v[192:195], v186 offset:56320
	global_load_lds_dwordx4 v[180:181], off
	v_lshl_add_u64 v[180:181], v[216:217], 0, s[28:29]
	s_mov_b32 m0, s17
	s_nop 0
	global_load_lds_dwordx4 v[180:181], off
	s_barrier
	s_waitcnt lgkmcnt(0)
	s_setprio 1
	s_waitcnt lgkmcnt(0)
	v_mfma_f32_16x16x32_bf16 v[76:79], v[56:59], v[144:147], v[76:79]
	v_mfma_f32_16x16x32_bf16 v[72:75], v[64:67], v[144:147], v[72:75]
	v_mfma_f32_16x16x32_bf16 v[44:47], v[56:59], v[152:155], v[44:47]
	v_mfma_f32_16x16x32_bf16 v[40:43], v[64:67], v[152:155], v[40:43]
	v_mfma_f32_16x16x32_bf16 v[28:31], v[56:59], v[172:175], v[28:31]
	v_mfma_f32_16x16x32_bf16 v[24:27], v[64:67], v[172:175], v[24:27]
	v_mfma_f32_16x16x32_bf16 v[12:15], v[56:59], v[188:191], v[12:15]
	v_mfma_f32_16x16x32_bf16 v[8:11], v[64:67], v[188:191], v[8:11]
	v_mfma_f32_16x16x32_bf16 v[76:79], v[60:63], v[148:151], v[76:79]
	v_mfma_f32_16x16x32_bf16 v[72:75], v[68:71], v[148:151], v[72:75]
	v_mfma_f32_16x16x32_bf16 v[44:47], v[60:63], v[156:159], v[44:47]
	v_mfma_f32_16x16x32_bf16 v[40:43], v[68:71], v[156:159], v[40:43]
	v_mfma_f32_16x16x32_bf16 v[28:31], v[60:63], v[176:179], v[28:31]
	v_mfma_f32_16x16x32_bf16 v[24:27], v[68:71], v[176:179], v[24:27]
	v_mfma_f32_16x16x32_bf16 v[12:15], v[60:63], v[192:195], v[12:15]
	v_mfma_f32_16x16x32_bf16 v[8:11], v[68:71], v[192:195], v[8:11]
	s_setprio 0
	s_barrier
	s_add_u32 s50, s52, 0x40080
	s_addc_u32 s51, s53, 0
	s_add_i32 s47, s54, s10
	v_lshl_add_u64 v[56:57], s[50:51], 0, v[160:161]
	s_mov_b32 m0, s47
	s_nop 0
	global_load_lds_dwordx4 v[56:57], off
	v_lshl_add_u64 v[56:57], s[50:51], 0, v[162:163]
	s_add_i32 m0, s47, 0x2000
	s_nop 0
	global_load_lds_dwordx4 v[56:57], off
	s_waitcnt vmcnt(6)
	s_barrier
	s_setprio 1
	v_mfma_f32_16x16x32_bf16 v[48:51], v[196:199], v[144:147], v[48:51]
	v_mfma_f32_16x16x32_bf16 v[68:71], v[200:203], v[148:151], v[48:51]
	v_mfma_f32_16x16x32_bf16 v[48:51], v[204:207], v[144:147], v[52:55]
	v_mfma_f32_16x16x32_bf16 v[36:39], v[196:199], v[152:155], v[36:39]
	v_mfma_f32_16x16x32_bf16 v[32:35], v[204:207], v[152:155], v[32:35]
	v_mfma_f32_16x16x32_bf16 v[20:23], v[196:199], v[172:175], v[20:23]
	v_mfma_f32_16x16x32_bf16 v[16:19], v[204:207], v[172:175], v[16:19]
	v_mfma_f32_16x16x32_bf16 v[4:7], v[196:199], v[188:191], v[4:7]
	v_mfma_f32_16x16x32_bf16 v[0:3], v[204:207], v[188:191], v[0:3]
	v_mfma_f32_16x16x32_bf16 v[64:67], v[208:211], v[148:151], v[48:51]
	v_mfma_f32_16x16x32_bf16 v[36:39], v[200:203], v[156:159], v[36:39]
	v_mfma_f32_16x16x32_bf16 v[32:35], v[208:211], v[156:159], v[32:35]
	v_mfma_f32_16x16x32_bf16 v[20:23], v[200:203], v[176:179], v[20:23]
	v_mfma_f32_16x16x32_bf16 v[16:19], v[208:211], v[176:179], v[16:19]
	v_mfma_f32_16x16x32_bf16 v[4:7], v[200:203], v[192:195], v[4:7]
	v_mfma_f32_16x16x32_bf16 v[0:3], v[208:211], v[192:195], v[0:3]
	s_setprio 0
	s_add_i32 s35, s35, 2
	s_add_u32 s48, s48, 0x100
	s_addc_u32 s49, s49, 0
	s_add_u32 s31, s31, 0x100
	s_addc_u32 s33, s33, 0
	s_cmp_gt_u32 s35, 13
	s_barrier
	s_cbranch_scc0 .LBB0_618
	v_and_b32_e32 v145, 64, v229
	v_xor_b32_e32 v144, 16, v229
	v_add_u32_e32 v145, 64, v145
	v_cmp_lt_i32_e32 vcc, v144, v145
	v_lshl_or_b32 v172, s46, 8, v184
	v_ashrrev_i32_e32 v173, 31, v172
	v_cndmask_b32_e32 v144, v229, v144, vcc
	v_lshl_add_u32 v174, s2, 8, v182
	v_lshlrev_b32_e32 v189, 2, v144
	v_xor_b32_e32 v144, 32, v229
	v_lshlrev_b64 v[206:207], 2, v[172:173]
	v_cmp_lt_i32_e32 vcc, v144, v145
	v_ashrrev_i32_e32 v175, 31, v174
	v_lshl_add_u64 v[176:177], s[44:45], 0, v[206:207]
	v_cndmask_b32_e32 v144, v229, v144, vcc
	v_lshlrev_b64 v[208:209], 12, v[174:175]
	v_lshl_add_u64 v[56:57], s[56:57], 0, v[206:207]
	v_lshlrev_b32_e32 v188, 2, v144
	v_lshl_add_u64 v[144:145], v[176:177], 0, v[208:209]
	global_load_dwordx4 v[52:55], v[56:57], off offset:16
	global_load_dwordx4 v[60:63], v[56:57], off
	global_load_dwordx4 v[48:51], v[56:57], off offset:144
	s_nop 0
	global_load_dwordx4 v[56:59], v[56:57], off offset:128
	s_nop 0
	global_load_dwordx4 v[190:193], v[144:145], off offset:16
	global_load_dwordx4 v[194:197], v[144:145], off
	global_load_dwordx4 v[198:201], v[144:145], off offset:144
	global_load_dwordx4 v[202:205], v[144:145], off offset:128
	v_or_b32_e32 v178, 16, v174
	v_ashrrev_i32_e32 v179, 31, v178
	v_lshlrev_b64 v[180:181], 12, v[178:179]
	v_lshl_add_u64 v[148:149], v[176:177], 0, v[180:181]
	global_load_dwordx4 v[152:155], v[148:149], off offset:16
	global_load_dwordx4 v[156:159], v[148:149], off
	global_load_dwordx4 v[144:147], v[148:149], off offset:144
	s_nop 0
	global_load_dwordx4 v[148:151], v[148:149], off offset:128
	s_waitcnt vmcnt(0)
	v_pk_add_f32 v[136:137], v[136:137], v[190:191]
	v_pk_add_f32 v[194:195], v[140:141], v[194:195]
	v_pk_add_f32 v[198:199], v[128:129], v[198:199]
	v_lshl_add_u64 v[128:129], s[78:79], 0, v[208:209]
	v_pk_add_f32 v[196:197], v[142:143], v[196:197]
	v_pk_mul_f32 v[212:213], v[194:195], v[194:195]
	v_pk_add_f32 v[190:191], v[132:133], v[202:203]
	v_lshl_add_u64 v[128:129], v[128:129], 0, v[206:207]
	v_pk_mul_f32 v[210:211], v[196:197], v[196:197]
	v_pk_add_f32 v[138:139], v[138:139], v[192:193]
	v_pk_add_f32 v[192:193], v[134:135], v[204:205]
	v_pk_mul_f32 v[204:205], v[190:191], v[190:191]
	v_pk_add_f32 v[200:201], v[130:131], v[200:201]
	global_store_dwordx4 v[128:129], v[194:197], off nt
	global_store_dwordx4 v[128:129], v[136:139], off offset:16 nt
	global_store_dwordx4 v[128:129], v[190:193], off offset:128 nt
	global_store_dwordx4 v[128:129], v[198:201], off offset:144 nt
	v_pk_mul_f32 v[134:135], v[56:57], v[190:191]
	v_add_f32_e32 v190, v212, v213
	v_add_f32_e32 v190, v210, v190
	v_pk_mul_f32 v[216:217], v[136:137], v[136:137]
	v_add_f32_e32 v190, v211, v190
	v_add_f32_e32 v190, v216, v190
	v_pk_mul_f32 v[214:215], v[138:139], v[138:139]
	v_add_f32_e32 v190, v217, v190
	v_add_f32_e32 v190, v214, v190
	v_add_f32_e32 v190, v215, v190
	v_add_f32_e32 v190, v204, v190
	v_pk_mul_f32 v[202:203], v[192:193], v[192:193]
	v_add_f32_e32 v190, v205, v190
	v_add_f32_e32 v190, v202, v190
	v_pk_mul_f32 v[220:221], v[198:199], v[198:199]
	v_add_f32_e32 v190, v203, v190
	v_add_f32_e32 v190, v220, v190
	v_pk_mul_f32 v[218:219], v[200:201], v[200:201]
	v_add_f32_e32 v190, v221, v190
	v_add_f32_e32 v190, v218, v190
	v_pk_mul_f32 v[128:129], v[62:63], v[196:197]
	v_add_f32_e32 v196, v219, v190
	v_lshlrev_b64 v[190:191], 11, v[174:175]
	v_pk_mul_f32 v[142:143], v[60:61], v[194:195]
	v_pk_mul_f32 v[130:131], v[52:53], v[136:137]
	v_pk_mul_f32 v[132:133], v[54:55], v[138:139]
	v_lshl_add_u64 v[190:191], s[24:25], 0, v[190:191]
	v_pk_mul_f32 v[136:137], v[58:59], v[192:193]
	v_pk_mul_f32 v[138:139], v[48:49], v[198:199]
	v_pk_mul_f32 v[140:141], v[50:51], v[200:201]
	v_lshl_add_u64 v[194:195], v[172:173], 1, v[190:191]
	v_cvt_pk_bf16_f32 v190, v142, v143
	v_cvt_pk_bf16_f32 v191, v128, v129
	v_cvt_pk_bf16_f32 v192, v130, v131
	v_cvt_pk_bf16_f32 v193, v132, v133
	v_cvt_pk_bf16_f32 v128, v134, v135
	v_cvt_pk_bf16_f32 v129, v136, v137
	v_cvt_pk_bf16_f32 v130, v138, v139
	v_cvt_pk_bf16_f32 v131, v140, v141
	global_store_dwordx4 v[194:195], v[190:193], off
	global_store_dwordx4 v[194:195], v[128:131], off offset:64
	ds_bpermute_b32 v128, v189, v196
	s_waitcnt lgkmcnt(0)
	v_add_f32_e32 v128, v196, v128
	ds_bpermute_b32 v129, v188, v128
	s_and_saveexec_b64 s[2:3], s[36:37]
	s_cbranch_execz .LBB0_621
	v_lshl_add_u64 v[130:131], v[174:175], 2, s[26:27]
	s_waitcnt lgkmcnt(0)
	v_add_f32_e32 v128, v128, v129
	global_atomic_add_f32 v[130:131], v128, off
.LBB0_621:
	s_or_b64 exec, exec, s[2:3]
	v_pk_add_f32 v[124:125], v[124:125], v[156:157]
	v_pk_add_f32 v[112:113], v[112:113], v[144:145]
	v_lshl_add_u64 v[144:145], s[78:79], 0, v[180:181]
	v_pk_add_f32 v[126:127], v[126:127], v[158:159]
	v_pk_mul_f32 v[130:131], v[124:125], v[124:125]
	v_lshl_add_u64 v[144:145], v[172:173], 2, v[144:145]
	s_waitcnt lgkmcnt(0)
	v_pk_mul_f32 v[128:129], v[126:127], v[126:127]
	v_pk_add_f32 v[122:123], v[122:123], v[154:155]
	v_pk_add_f32 v[120:121], v[120:121], v[152:153]
	v_pk_add_f32 v[118:119], v[118:119], v[150:151]
	v_pk_add_f32 v[116:117], v[116:117], v[148:149]
	v_pk_add_f32 v[114:115], v[114:115], v[146:147]
	v_pk_mul_f32 v[142:143], v[112:113], v[112:113]
	global_store_dwordx4 v[144:145], v[124:127], off nt
	global_store_dwordx4 v[144:145], v[120:123], off offset:16 nt
	global_store_dwordx4 v[144:145], v[116:119], off offset:128 nt
	global_store_dwordx4 v[144:145], v[112:115], off offset:144 nt
	v_pk_mul_f32 v[148:149], v[48:49], v[112:113]
	v_pk_mul_f32 v[134:135], v[120:121], v[120:121]
	v_add_f32_e32 v112, v130, v131
	v_add_f32_e32 v112, v128, v112
	v_add_f32_e32 v112, v129, v112
	v_add_f32_e32 v112, v134, v112
	v_pk_mul_f32 v[132:133], v[122:123], v[122:123]
	v_add_f32_e32 v112, v135, v112
	v_add_f32_e32 v112, v132, v112
	v_pk_mul_f32 v[138:139], v[116:117], v[116:117]
	v_add_f32_e32 v112, v133, v112
	v_add_f32_e32 v112, v138, v112
	v_pk_mul_f32 v[136:137], v[118:119], v[118:119]
	v_add_f32_e32 v112, v139, v112
	v_add_f32_e32 v112, v136, v112
	v_add_f32_e32 v112, v137, v112
	v_add_f32_e32 v112, v142, v112
	v_pk_mul_f32 v[140:141], v[114:115], v[114:115]
	v_add_f32_e32 v112, v143, v112
	v_add_f32_e32 v112, v140, v112
	v_add_f32_e32 v130, v141, v112
	v_lshlrev_b64 v[112:113], 11, v[178:179]
	v_lshl_add_u64 v[112:113], s[24:25], 0, v[112:113]
	v_lshl_add_u64 v[128:129], v[172:173], 1, v[112:113]
	ds_bpermute_b32 v112, v189, v130
	v_pk_mul_f32 v[124:125], v[60:61], v[124:125]
	v_pk_mul_f32 v[126:127], v[62:63], v[126:127]
	v_pk_mul_f32 v[120:121], v[52:53], v[120:121]
	v_pk_mul_f32 v[122:123], v[54:55], v[122:123]
	s_waitcnt lgkmcnt(0)
	v_add_f32_e32 v112, v130, v112
	ds_bpermute_b32 v113, v188, v112
	v_pk_mul_f32 v[144:145], v[56:57], v[116:117]
	v_pk_mul_f32 v[146:147], v[58:59], v[118:119]
	v_pk_mul_f32 v[150:151], v[50:51], v[114:115]
	v_cvt_pk_bf16_f32 v114, v124, v125
	v_cvt_pk_bf16_f32 v115, v126, v127
	v_cvt_pk_bf16_f32 v116, v120, v121
	v_cvt_pk_bf16_f32 v117, v122, v123
	v_cvt_pk_bf16_f32 v118, v144, v145
	v_cvt_pk_bf16_f32 v119, v146, v147
	v_cvt_pk_bf16_f32 v120, v148, v149
	v_cvt_pk_bf16_f32 v121, v150, v151
	global_store_dwordx4 v[128:129], v[114:117], off
	global_store_dwordx4 v[128:129], v[118:121], off offset:64
	s_and_saveexec_b64 s[2:3], s[36:37]
	s_cbranch_execz .LBB0_623
	v_lshl_add_u64 v[114:115], v[178:179], 2, s[26:27]
	s_waitcnt lgkmcnt(0)
	v_add_f32_e32 v112, v112, v113
	global_atomic_add_f32 v[114:115], v112, off
.LBB0_623:
	s_or_b64 exec, exec, s[2:3]
	v_or_b32_e32 v132, 32, v174
	v_ashrrev_i32_e32 v133, 31, v132
	v_lshlrev_b64 v[150:151], 12, v[132:133]
	s_waitcnt lgkmcnt(0)
	v_lshl_add_u64 v[112:113], v[176:177], 0, v[150:151]
	global_load_dwordx4 v[134:137], v[112:113], off offset:16
	global_load_dwordx4 v[138:141], v[112:113], off
	global_load_dwordx4 v[142:145], v[112:113], off offset:144
	global_load_dwordx4 v[146:149], v[112:113], off offset:128
	v_or_b32_e32 v128, 48, v174
	v_ashrrev_i32_e32 v129, 31, v128
	v_lshlrev_b64 v[130:131], 12, v[128:129]
	v_lshl_add_u64 v[116:117], v[176:177], 0, v[130:131]
	global_load_dwordx4 v[120:123], v[116:117], off offset:16
	global_load_dwordx4 v[124:127], v[116:117], off
	global_load_dwordx4 v[112:115], v[116:117], off offset:144
	s_nop 0
	global_load_dwordx4 v[116:119], v[116:117], off offset:128
	s_waitcnt vmcnt(7)
	v_pk_add_f32 v[104:105], v[104:105], v[134:135]
	s_waitcnt vmcnt(6)
	v_pk_add_f32 v[138:139], v[108:109], v[138:139]
	s_waitcnt vmcnt(5)
	v_pk_add_f32 v[142:143], v[96:97], v[142:143]
	v_lshl_add_u64 v[96:97], s[78:79], 0, v[150:151]
	v_pk_add_f32 v[140:141], v[110:111], v[140:141]
	v_pk_mul_f32 v[154:155], v[138:139], v[138:139]
	s_waitcnt vmcnt(4)
	v_pk_add_f32 v[134:135], v[100:101], v[146:147]
	v_lshl_add_u64 v[96:97], v[172:173], 2, v[96:97]
	v_pk_mul_f32 v[152:153], v[140:141], v[140:141]
	v_pk_add_f32 v[106:107], v[106:107], v[136:137]
	v_pk_add_f32 v[136:137], v[102:103], v[148:149]
	v_pk_mul_f32 v[148:149], v[134:135], v[134:135]
	v_pk_add_f32 v[144:145], v[98:99], v[144:145]
	global_store_dwordx4 v[96:97], v[138:141], off nt
	global_store_dwordx4 v[96:97], v[104:107], off offset:16 nt
	global_store_dwordx4 v[96:97], v[134:137], off offset:128 nt
	global_store_dwordx4 v[96:97], v[142:145], off offset:144 nt
	v_pk_mul_f32 v[102:103], v[56:57], v[134:135]
	v_add_f32_e32 v134, v154, v155
	v_add_f32_e32 v134, v152, v134
	v_pk_mul_f32 v[158:159], v[104:105], v[104:105]
	v_add_f32_e32 v134, v153, v134
	v_add_f32_e32 v134, v158, v134
	v_pk_mul_f32 v[156:157], v[106:107], v[106:107]
	v_add_f32_e32 v134, v159, v134
	v_add_f32_e32 v134, v156, v134
	v_add_f32_e32 v134, v157, v134
	v_add_f32_e32 v134, v148, v134
	v_pk_mul_f32 v[146:147], v[136:137], v[136:137]
	v_add_f32_e32 v134, v149, v134
	v_add_f32_e32 v134, v146, v134
	v_pk_mul_f32 v[180:181], v[142:143], v[142:143]
	v_add_f32_e32 v134, v147, v134
	v_add_f32_e32 v134, v180, v134
	v_pk_mul_f32 v[178:179], v[144:145], v[144:145]
	v_add_f32_e32 v134, v181, v134
	v_add_f32_e32 v134, v178, v134
	v_pk_mul_f32 v[96:97], v[62:63], v[140:141]
	v_add_f32_e32 v140, v179, v134
	v_lshlrev_b64 v[134:135], 11, v[132:133]
	v_pk_mul_f32 v[110:111], v[60:61], v[138:139]
	v_pk_mul_f32 v[98:99], v[52:53], v[104:105]
	v_pk_mul_f32 v[100:101], v[54:55], v[106:107]
	v_lshl_add_u64 v[134:135], s[24:25], 0, v[134:135]
	v_pk_mul_f32 v[104:105], v[58:59], v[136:137]
	v_pk_mul_f32 v[106:107], v[48:49], v[142:143]
	v_pk_mul_f32 v[108:109], v[50:51], v[144:145]
	v_lshl_add_u64 v[138:139], v[172:173], 1, v[134:135]
	v_cvt_pk_bf16_f32 v134, v110, v111
	v_cvt_pk_bf16_f32 v135, v96, v97
	v_cvt_pk_bf16_f32 v136, v98, v99
	v_cvt_pk_bf16_f32 v137, v100, v101
	v_cvt_pk_bf16_f32 v96, v102, v103
	v_cvt_pk_bf16_f32 v97, v104, v105
	v_cvt_pk_bf16_f32 v98, v106, v107
	v_cvt_pk_bf16_f32 v99, v108, v109
	global_store_dwordx4 v[138:139], v[134:137], off
	global_store_dwordx4 v[138:139], v[96:99], off offset:64
	ds_bpermute_b32 v96, v189, v140
	s_waitcnt lgkmcnt(0)
	v_add_f32_e32 v96, v140, v96
	ds_bpermute_b32 v97, v188, v96
	s_and_saveexec_b64 s[2:3], s[36:37]
	s_cbranch_execz .LBB0_625
	v_lshl_add_u64 v[98:99], v[132:133], 2, s[26:27]
	s_waitcnt lgkmcnt(0)
	v_add_f32_e32 v96, v96, v97
	global_atomic_add_f32 v[98:99], v96, off
.LBB0_625:
	s_or_b64 exec, exec, s[2:3]
	s_waitcnt vmcnt(8)
	v_pk_add_f32 v[92:93], v[92:93], v[124:125]
	s_waitcnt vmcnt(7)
	v_pk_add_f32 v[80:81], v[80:81], v[112:113]
	v_lshl_add_u64 v[112:113], s[78:79], 0, v[130:131]
	v_pk_add_f32 v[94:95], v[94:95], v[126:127]
	v_pk_mul_f32 v[98:99], v[92:93], v[92:93]
	v_lshl_add_u64 v[112:113], v[172:173], 2, v[112:113]
	s_waitcnt lgkmcnt(0)
	v_pk_mul_f32 v[96:97], v[94:95], v[94:95]
	v_pk_add_f32 v[90:91], v[90:91], v[122:123]
	v_pk_add_f32 v[88:89], v[88:89], v[120:121]
	s_waitcnt vmcnt(6)
	v_pk_add_f32 v[86:87], v[86:87], v[118:119]
	v_pk_add_f32 v[84:85], v[84:85], v[116:117]
	v_pk_add_f32 v[82:83], v[82:83], v[114:115]
	v_pk_mul_f32 v[110:111], v[80:81], v[80:81]
	global_store_dwordx4 v[112:113], v[92:95], off nt
	global_store_dwordx4 v[112:113], v[88:91], off offset:16 nt
	global_store_dwordx4 v[112:113], v[84:87], off offset:128 nt
	global_store_dwordx4 v[112:113], v[80:83], off offset:144 nt
	v_pk_mul_f32 v[116:117], v[48:49], v[80:81]
	v_pk_mul_f32 v[102:103], v[88:89], v[88:89]
	v_add_f32_e32 v80, v98, v99
	v_add_f32_e32 v80, v96, v80
	v_add_f32_e32 v80, v97, v80
	v_add_f32_e32 v80, v102, v80
	v_pk_mul_f32 v[100:101], v[90:91], v[90:91]
	v_add_f32_e32 v80, v103, v80
	v_add_f32_e32 v80, v100, v80
	v_pk_mul_f32 v[106:107], v[84:85], v[84:85]
	v_add_f32_e32 v80, v101, v80
	v_add_f32_e32 v80, v106, v80
	v_pk_mul_f32 v[104:105], v[86:87], v[86:87]
	v_add_f32_e32 v80, v107, v80
	v_add_f32_e32 v80, v104, v80
	v_add_f32_e32 v80, v105, v80
	v_add_f32_e32 v80, v110, v80
	v_pk_mul_f32 v[108:109], v[82:83], v[82:83]
	v_add_f32_e32 v80, v111, v80
	v_add_f32_e32 v80, v108, v80
	v_add_f32_e32 v98, v109, v80
	v_lshlrev_b64 v[80:81], 11, v[128:129]
	v_lshl_add_u64 v[80:81], s[24:25], 0, v[80:81]
	v_lshl_add_u64 v[96:97], v[172:173], 1, v[80:81]
	ds_bpermute_b32 v80, v189, v98
	v_pk_mul_f32 v[92:93], v[60:61], v[92:93]
	v_pk_mul_f32 v[94:95], v[62:63], v[94:95]
	v_pk_mul_f32 v[88:89], v[52:53], v[88:89]
	v_pk_mul_f32 v[90:91], v[54:55], v[90:91]
	s_waitcnt lgkmcnt(0)
	v_add_f32_e32 v80, v98, v80
	ds_bpermute_b32 v81, v188, v80
	v_pk_mul_f32 v[112:113], v[56:57], v[84:85]
	v_pk_mul_f32 v[114:115], v[58:59], v[86:87]
	v_pk_mul_f32 v[118:119], v[50:51], v[82:83]
	v_cvt_pk_bf16_f32 v82, v92, v93
	v_cvt_pk_bf16_f32 v83, v94, v95
	v_cvt_pk_bf16_f32 v84, v88, v89
	v_cvt_pk_bf16_f32 v85, v90, v91
	v_cvt_pk_bf16_f32 v86, v112, v113
	v_cvt_pk_bf16_f32 v87, v114, v115
	v_cvt_pk_bf16_f32 v88, v116, v117
	v_cvt_pk_bf16_f32 v89, v118, v119
	global_store_dwordx4 v[96:97], v[82:85], off
	global_store_dwordx4 v[96:97], v[86:89], off offset:64
	s_and_saveexec_b64 s[2:3], s[36:37]
	s_cbranch_execz .LBB0_627
	v_lshl_add_u64 v[82:83], v[128:129], 2, s[26:27]
	s_waitcnt lgkmcnt(0)
	v_add_f32_e32 v80, v80, v81
	global_atomic_add_f32 v[82:83], v80, off
.LBB0_627:
	s_or_b64 exec, exec, s[2:3]
	v_add_u32_e32 v100, 0x80, v174
	v_ashrrev_i32_e32 v101, 31, v100
	v_lshlrev_b64 v[118:119], 12, v[100:101]
	s_waitcnt lgkmcnt(0)
	v_lshl_add_u64 v[80:81], v[176:177], 0, v[118:119]
	global_load_dwordx4 v[102:105], v[80:81], off offset:16
	global_load_dwordx4 v[106:109], v[80:81], off
	global_load_dwordx4 v[110:113], v[80:81], off offset:144
	global_load_dwordx4 v[114:117], v[80:81], off offset:128
	v_add_u32_e32 v96, 0x90, v174
	v_ashrrev_i32_e32 v97, 31, v96
	v_lshlrev_b64 v[98:99], 12, v[96:97]
	v_lshl_add_u64 v[84:85], v[176:177], 0, v[98:99]
	global_load_dwordx4 v[88:91], v[84:85], off offset:16
	global_load_dwordx4 v[92:95], v[84:85], off
	global_load_dwordx4 v[80:83], v[84:85], off offset:144
	s_nop 0
	global_load_dwordx4 v[84:87], v[84:85], off offset:128
	s_waitcnt vmcnt(7)
	v_pk_add_f32 v[72:73], v[72:73], v[102:103]
	s_waitcnt vmcnt(6)
	v_pk_add_f32 v[106:107], v[76:77], v[106:107]
	s_waitcnt vmcnt(5)
	v_pk_add_f32 v[110:111], v[64:65], v[110:111]
	v_lshl_add_u64 v[64:65], s[78:79], 0, v[118:119]
	v_pk_add_f32 v[108:109], v[78:79], v[108:109]
	v_pk_mul_f32 v[122:123], v[106:107], v[106:107]
	s_waitcnt vmcnt(4)
	v_pk_add_f32 v[102:103], v[68:69], v[114:115]
	v_lshl_add_u64 v[64:65], v[172:173], 2, v[64:65]
	v_pk_mul_f32 v[120:121], v[108:109], v[108:109]
	v_pk_add_f32 v[74:75], v[74:75], v[104:105]
	v_pk_add_f32 v[104:105], v[70:71], v[116:117]
	v_pk_mul_f32 v[116:117], v[102:103], v[102:103]
	v_pk_add_f32 v[112:113], v[66:67], v[112:113]
	global_store_dwordx4 v[64:65], v[106:109], off nt
	global_store_dwordx4 v[64:65], v[72:75], off offset:16 nt
	global_store_dwordx4 v[64:65], v[102:105], off offset:128 nt
	global_store_dwordx4 v[64:65], v[110:113], off offset:144 nt
	v_pk_mul_f32 v[70:71], v[56:57], v[102:103]
	v_add_f32_e32 v102, v122, v123
	v_add_f32_e32 v102, v120, v102
	v_pk_mul_f32 v[126:127], v[72:73], v[72:73]
	v_add_f32_e32 v102, v121, v102
	v_add_f32_e32 v102, v126, v102
	v_pk_mul_f32 v[124:125], v[74:75], v[74:75]
	v_add_f32_e32 v102, v127, v102
	v_add_f32_e32 v102, v124, v102
	v_add_f32_e32 v102, v125, v102
	v_add_f32_e32 v102, v116, v102
	v_pk_mul_f32 v[114:115], v[104:105], v[104:105]
	v_add_f32_e32 v102, v117, v102
	v_add_f32_e32 v102, v114, v102
	v_pk_mul_f32 v[130:131], v[110:111], v[110:111]
	v_add_f32_e32 v102, v115, v102
	v_add_f32_e32 v102, v130, v102
	v_pk_mul_f32 v[128:129], v[112:113], v[112:113]
	v_add_f32_e32 v102, v131, v102
	v_add_f32_e32 v102, v128, v102
	v_pk_mul_f32 v[64:65], v[62:63], v[108:109]
	v_add_f32_e32 v108, v129, v102
	v_lshlrev_b64 v[102:103], 11, v[100:101]
	v_pk_mul_f32 v[78:79], v[60:61], v[106:107]
	v_pk_mul_f32 v[66:67], v[52:53], v[72:73]
	v_pk_mul_f32 v[68:69], v[54:55], v[74:75]
	v_lshl_add_u64 v[102:103], s[24:25], 0, v[102:103]
	v_pk_mul_f32 v[72:73], v[58:59], v[104:105]
	v_pk_mul_f32 v[74:75], v[48:49], v[110:111]
	v_pk_mul_f32 v[76:77], v[50:51], v[112:113]
	v_lshl_add_u64 v[106:107], v[172:173], 1, v[102:103]
	v_cvt_pk_bf16_f32 v102, v78, v79
	v_cvt_pk_bf16_f32 v103, v64, v65
	v_cvt_pk_bf16_f32 v104, v66, v67
	v_cvt_pk_bf16_f32 v105, v68, v69
	v_cvt_pk_bf16_f32 v64, v70, v71
	v_cvt_pk_bf16_f32 v65, v72, v73
	v_cvt_pk_bf16_f32 v66, v74, v75
	v_cvt_pk_bf16_f32 v67, v76, v77
	global_store_dwordx4 v[106:107], v[102:105], off
	global_store_dwordx4 v[106:107], v[64:67], off offset:64
	ds_bpermute_b32 v64, v189, v108
	s_waitcnt lgkmcnt(0)
	v_add_f32_e32 v64, v108, v64
	ds_bpermute_b32 v65, v188, v64
	s_and_saveexec_b64 s[2:3], s[36:37]
	s_cbranch_execz .LBB0_629
	v_lshl_add_u64 v[66:67], v[100:101], 2, s[26:27]
	s_waitcnt lgkmcnt(0)
	v_add_f32_e32 v64, v64, v65
	global_atomic_add_f32 v[66:67], v64, off
.LBB0_629:
	s_or_b64 exec, exec, s[2:3]
	s_waitcnt vmcnt(8)
	v_pk_add_f32 v[44:45], v[44:45], v[92:93]
	s_waitcnt vmcnt(7)
	v_pk_add_f32 v[32:33], v[32:33], v[80:81]
	v_lshl_add_u64 v[80:81], s[78:79], 0, v[98:99]
	v_pk_add_f32 v[46:47], v[46:47], v[94:95]
	v_pk_mul_f32 v[66:67], v[44:45], v[44:45]
	v_lshl_add_u64 v[80:81], v[172:173], 2, v[80:81]
	s_waitcnt lgkmcnt(0)
	v_pk_mul_f32 v[64:65], v[46:47], v[46:47]
	v_pk_add_f32 v[42:43], v[42:43], v[90:91]
	v_pk_add_f32 v[40:41], v[40:41], v[88:89]
	s_waitcnt vmcnt(6)
	v_pk_add_f32 v[38:39], v[38:39], v[86:87]
	v_pk_add_f32 v[36:37], v[36:37], v[84:85]
	v_pk_add_f32 v[34:35], v[34:35], v[82:83]
	v_pk_mul_f32 v[78:79], v[32:33], v[32:33]
	global_store_dwordx4 v[80:81], v[44:47], off nt
	global_store_dwordx4 v[80:81], v[40:43], off offset:16 nt
	global_store_dwordx4 v[80:81], v[36:39], off offset:128 nt
	global_store_dwordx4 v[80:81], v[32:35], off offset:144 nt
	v_pk_mul_f32 v[84:85], v[48:49], v[32:33]
	v_pk_mul_f32 v[70:71], v[40:41], v[40:41]
	v_add_f32_e32 v32, v66, v67
	v_add_f32_e32 v32, v64, v32
	v_add_f32_e32 v32, v65, v32
	v_add_f32_e32 v32, v70, v32
	v_pk_mul_f32 v[68:69], v[42:43], v[42:43]
	v_add_f32_e32 v32, v71, v32
	v_add_f32_e32 v32, v68, v32
	v_pk_mul_f32 v[74:75], v[36:37], v[36:37]
	v_add_f32_e32 v32, v69, v32
	v_add_f32_e32 v32, v74, v32
	v_pk_mul_f32 v[72:73], v[38:39], v[38:39]
	v_add_f32_e32 v32, v75, v32
	v_add_f32_e32 v32, v72, v32
	v_add_f32_e32 v32, v73, v32
	v_add_f32_e32 v32, v78, v32
	v_pk_mul_f32 v[76:77], v[34:35], v[34:35]
	v_add_f32_e32 v32, v79, v32
	v_add_f32_e32 v32, v76, v32
	v_add_f32_e32 v66, v77, v32
	v_lshlrev_b64 v[32:33], 11, v[96:97]
	v_lshl_add_u64 v[32:33], s[24:25], 0, v[32:33]
	v_lshl_add_u64 v[64:65], v[172:173], 1, v[32:33]
	ds_bpermute_b32 v32, v189, v66
	v_pk_mul_f32 v[44:45], v[60:61], v[44:45]
	v_pk_mul_f32 v[46:47], v[62:63], v[46:47]
	v_pk_mul_f32 v[40:41], v[52:53], v[40:41]
	v_pk_mul_f32 v[42:43], v[54:55], v[42:43]
	s_waitcnt lgkmcnt(0)
	v_add_f32_e32 v32, v66, v32
	ds_bpermute_b32 v33, v188, v32
	v_pk_mul_f32 v[80:81], v[56:57], v[36:37]
	v_pk_mul_f32 v[82:83], v[58:59], v[38:39]
	v_pk_mul_f32 v[86:87], v[50:51], v[34:35]
	v_cvt_pk_bf16_f32 v34, v44, v45
	v_cvt_pk_bf16_f32 v35, v46, v47
	v_cvt_pk_bf16_f32 v36, v40, v41
	v_cvt_pk_bf16_f32 v37, v42, v43
	v_cvt_pk_bf16_f32 v38, v80, v81
	v_cvt_pk_bf16_f32 v39, v82, v83
	v_cvt_pk_bf16_f32 v40, v84, v85
	v_cvt_pk_bf16_f32 v41, v86, v87
	global_store_dwordx4 v[64:65], v[34:37], off
	global_store_dwordx4 v[64:65], v[38:41], off offset:64
	s_and_saveexec_b64 s[2:3], s[36:37]
	s_cbranch_execz .LBB0_631
	v_lshl_add_u64 v[34:35], v[96:97], 2, s[26:27]
	s_waitcnt lgkmcnt(0)
	v_add_f32_e32 v32, v32, v33
	global_atomic_add_f32 v[34:35], v32, off
.LBB0_631:
	s_or_b64 exec, exec, s[2:3]
	v_add_u32_e32 v68, 0xa0, v174
	v_ashrrev_i32_e32 v69, 31, v68
	v_lshlrev_b64 v[86:87], 12, v[68:69]
	s_waitcnt lgkmcnt(0)
	v_lshl_add_u64 v[32:33], v[176:177], 0, v[86:87]
	global_load_dwordx4 v[70:73], v[32:33], off offset:16
	global_load_dwordx4 v[74:77], v[32:33], off
	global_load_dwordx4 v[78:81], v[32:33], off offset:144
	global_load_dwordx4 v[82:85], v[32:33], off offset:128
	v_add_u32_e32 v64, 0xb0, v174
	v_ashrrev_i32_e32 v65, 31, v64
	v_lshlrev_b64 v[66:67], 12, v[64:65]
	v_lshl_add_u64 v[36:37], v[176:177], 0, v[66:67]
	global_load_dwordx4 v[40:43], v[36:37], off offset:16
	global_load_dwordx4 v[44:47], v[36:37], off
	global_load_dwordx4 v[32:35], v[36:37], off offset:144
	s_nop 0
	global_load_dwordx4 v[36:39], v[36:37], off offset:128
	s_waitcnt vmcnt(7)
	v_pk_add_f32 v[24:25], v[24:25], v[70:71]
	s_waitcnt vmcnt(6)
	v_pk_add_f32 v[74:75], v[28:29], v[74:75]
	s_waitcnt vmcnt(5)
	v_pk_add_f32 v[78:79], v[16:17], v[78:79]
	v_lshl_add_u64 v[16:17], s[78:79], 0, v[86:87]
	v_pk_add_f32 v[76:77], v[30:31], v[76:77]
	v_pk_mul_f32 v[90:91], v[74:75], v[74:75]
	s_waitcnt vmcnt(4)
	v_pk_add_f32 v[70:71], v[20:21], v[82:83]
	v_lshl_add_u64 v[16:17], v[172:173], 2, v[16:17]
	v_pk_mul_f32 v[88:89], v[76:77], v[76:77]
	v_pk_add_f32 v[26:27], v[26:27], v[72:73]
	v_pk_add_f32 v[72:73], v[22:23], v[84:85]
	v_pk_mul_f32 v[84:85], v[70:71], v[70:71]
	v_pk_add_f32 v[80:81], v[18:19], v[80:81]
	global_store_dwordx4 v[16:17], v[74:77], off nt
	global_store_dwordx4 v[16:17], v[24:27], off offset:16 nt
	global_store_dwordx4 v[16:17], v[70:73], off offset:128 nt
	global_store_dwordx4 v[16:17], v[78:81], off offset:144 nt
	v_pk_mul_f32 v[22:23], v[56:57], v[70:71]
	v_add_f32_e32 v70, v90, v91
	v_add_f32_e32 v70, v88, v70
	v_pk_mul_f32 v[94:95], v[24:25], v[24:25]
	v_add_f32_e32 v70, v89, v70
	v_add_f32_e32 v70, v94, v70
	v_pk_mul_f32 v[92:93], v[26:27], v[26:27]
	v_add_f32_e32 v70, v95, v70
	v_add_f32_e32 v70, v92, v70
	v_add_f32_e32 v70, v93, v70
	v_add_f32_e32 v70, v84, v70
	v_pk_mul_f32 v[82:83], v[72:73], v[72:73]
	v_add_f32_e32 v70, v85, v70
	v_add_f32_e32 v70, v82, v70
	v_pk_mul_f32 v[98:99], v[78:79], v[78:79]
	v_add_f32_e32 v70, v83, v70
	v_add_f32_e32 v70, v98, v70
	v_pk_mul_f32 v[96:97], v[80:81], v[80:81]
	v_add_f32_e32 v70, v99, v70
	v_add_f32_e32 v70, v96, v70
	v_pk_mul_f32 v[16:17], v[62:63], v[76:77]
	v_add_f32_e32 v76, v97, v70
	v_lshlrev_b64 v[70:71], 11, v[68:69]
	v_pk_mul_f32 v[30:31], v[60:61], v[74:75]
	v_pk_mul_f32 v[18:19], v[52:53], v[24:25]
	v_pk_mul_f32 v[20:21], v[54:55], v[26:27]
	v_lshl_add_u64 v[70:71], s[24:25], 0, v[70:71]
	v_pk_mul_f32 v[24:25], v[58:59], v[72:73]
	v_pk_mul_f32 v[26:27], v[48:49], v[78:79]
	v_pk_mul_f32 v[28:29], v[50:51], v[80:81]
	v_lshl_add_u64 v[74:75], v[172:173], 1, v[70:71]
	v_cvt_pk_bf16_f32 v70, v30, v31
	v_cvt_pk_bf16_f32 v71, v16, v17
	v_cvt_pk_bf16_f32 v72, v18, v19
	v_cvt_pk_bf16_f32 v73, v20, v21
	v_cvt_pk_bf16_f32 v16, v22, v23
	v_cvt_pk_bf16_f32 v17, v24, v25
	v_cvt_pk_bf16_f32 v18, v26, v27
	v_cvt_pk_bf16_f32 v19, v28, v29
	global_store_dwordx4 v[74:75], v[70:73], off
	global_store_dwordx4 v[74:75], v[16:19], off offset:64
	ds_bpermute_b32 v16, v189, v76
	s_waitcnt lgkmcnt(0)
	v_add_f32_e32 v16, v76, v16
	ds_bpermute_b32 v17, v188, v16
	s_and_saveexec_b64 s[2:3], s[36:37]
	s_cbranch_execz .LBB0_633
	v_lshl_add_u64 v[18:19], v[68:69], 2, s[26:27]
	s_waitcnt lgkmcnt(0)
	v_add_f32_e32 v16, v16, v17
	global_atomic_add_f32 v[18:19], v16, off
.LBB0_633:
	s_or_b64 exec, exec, s[2:3]
	s_waitcnt vmcnt(8)
	v_pk_add_f32 v[12:13], v[12:13], v[44:45]
	s_waitcnt vmcnt(7)
	v_pk_add_f32 v[0:1], v[0:1], v[32:33]
	v_lshl_add_u64 v[32:33], s[78:79], 0, v[66:67]
	v_pk_add_f32 v[14:15], v[14:15], v[46:47]
	v_pk_mul_f32 v[18:19], v[12:13], v[12:13]
	v_lshl_add_u64 v[32:33], v[172:173], 2, v[32:33]
	s_waitcnt lgkmcnt(0)
	v_pk_mul_f32 v[16:17], v[14:15], v[14:15]
	v_pk_add_f32 v[10:11], v[10:11], v[42:43]
	v_pk_add_f32 v[8:9], v[8:9], v[40:41]
	s_waitcnt vmcnt(6)
	v_pk_add_f32 v[6:7], v[6:7], v[38:39]
	v_pk_add_f32 v[4:5], v[4:5], v[36:37]
	v_pk_add_f32 v[2:3], v[2:3], v[34:35]
	v_pk_mul_f32 v[30:31], v[0:1], v[0:1]
	global_store_dwordx4 v[32:33], v[12:15], off nt
	global_store_dwordx4 v[32:33], v[8:11], off offset:16 nt
	global_store_dwordx4 v[32:33], v[4:7], off offset:128 nt
	global_store_dwordx4 v[32:33], v[0:3], off offset:144 nt
	v_pk_mul_f32 v[36:37], v[48:49], v[0:1]
	v_pk_mul_f32 v[22:23], v[8:9], v[8:9]
	v_add_f32_e32 v0, v18, v19
	v_add_f32_e32 v0, v16, v0
	v_add_f32_e32 v0, v17, v0
	v_add_f32_e32 v0, v22, v0
	v_pk_mul_f32 v[20:21], v[10:11], v[10:11]
	v_add_f32_e32 v0, v23, v0
	v_add_f32_e32 v0, v20, v0
	v_pk_mul_f32 v[26:27], v[4:5], v[4:5]
	v_add_f32_e32 v0, v21, v0
	v_add_f32_e32 v0, v26, v0
	v_pk_mul_f32 v[24:25], v[6:7], v[6:7]
	v_add_f32_e32 v0, v27, v0
	v_add_f32_e32 v0, v24, v0
	v_add_f32_e32 v0, v25, v0
	v_add_f32_e32 v0, v30, v0
	v_pk_mul_f32 v[28:29], v[2:3], v[2:3]
	v_add_f32_e32 v0, v31, v0
	v_add_f32_e32 v0, v28, v0
	v_add_f32_e32 v18, v29, v0
	v_lshlrev_b64 v[0:1], 11, v[64:65]
	v_lshl_add_u64 v[0:1], s[24:25], 0, v[0:1]
	v_lshl_add_u64 v[16:17], v[172:173], 1, v[0:1]
	ds_bpermute_b32 v0, v189, v18
	v_pk_mul_f32 v[12:13], v[60:61], v[12:13]
	v_pk_mul_f32 v[14:15], v[62:63], v[14:15]
	v_pk_mul_f32 v[8:9], v[52:53], v[8:9]
	v_pk_mul_f32 v[10:11], v[54:55], v[10:11]
	s_waitcnt lgkmcnt(0)
	v_add_f32_e32 v0, v18, v0
	ds_bpermute_b32 v1, v188, v0
	v_pk_mul_f32 v[32:33], v[56:57], v[4:5]
	v_pk_mul_f32 v[34:35], v[58:59], v[6:7]
	v_pk_mul_f32 v[38:39], v[50:51], v[2:3]
	v_cvt_pk_bf16_f32 v2, v12, v13
	v_cvt_pk_bf16_f32 v3, v14, v15
	v_cvt_pk_bf16_f32 v4, v8, v9
	v_cvt_pk_bf16_f32 v5, v10, v11
	v_cvt_pk_bf16_f32 v6, v32, v33
	v_cvt_pk_bf16_f32 v7, v34, v35
	v_cvt_pk_bf16_f32 v8, v36, v37
	v_cvt_pk_bf16_f32 v9, v38, v39
	global_store_dwordx4 v[16:17], v[2:5], off
	global_store_dwordx4 v[16:17], v[6:9], off offset:64
	s_and_saveexec_b64 s[2:3], s[36:37]
	s_cbranch_execz .LBB0_610
	v_lshl_add_u64 v[2:3], v[64:65], 2, s[26:27]
	s_waitcnt lgkmcnt(0)
	v_add_f32_e32 v0, v0, v1
	global_atomic_add_f32 v[2:3], v0, off
	s_branch .LBB0_610
